# FFN-up sample epilogue: 32 conv-state stores sunk below the first load group wait (vmcnt(0) no longer waits for store acks)
# baseline (speedup 1.0000x reference)
; #define LAS __attribute__((address_space(3)))
;     __device__ __forceinline__ void prescale_publish(f32x4 (&acc)[2][2][4][2], const float (&rs)[2][4], int wr, int wc, int fr, int fq) const {
; #pragma unroll
;         for (int ai = 0; ai < 2; ++ai)
; #pragma unroll
;             for (int m = 0; m < 4; ++m) { const float r1 = rsqrtf(rs[ai][m] * (1.f / D) + EPS);
; #pragma unroll
;                 for (int bj = 0; bj < 2; ++bj)
; #pragma unroll
;                     for (int n = 0; n < 2; ++n) acc[ai][bj][m][n] = acc[ai][bj][m][n] * r1; }
;         if (fr >= 14) {
; #pragma unroll
;             for (int ai = 0; ai < 2; ++ai)
; #pragma unroll
;                 for (int bj = 0; bj < 2; ++bj)
; #pragma unroll
;                     for (int n = 0; n < 2; ++n) *(LAS f32x4*)(bnd + ((ai * 2 + wr) * 2 + (fr - 14)) * 256 + bj * 128 + wc * 32 + 8 * fq + 4 * n) = acc[ai][bj][3][n];
;         }
;         asm volatile("s_waitcnt lgkmcnt(0)" ::: "memory"); __builtin_amdgcn_s_barrier(); asm volatile("" ::: "memory");
;     __device__ __forceinline__ void sample(f32x4 (&acc)[2][2][4][2], const Unit& u, int row0t, int wr, int wc, int fr, int fq) const {
;         const int t = fr & 7, sql = ((row0t - NPROMPT + wr * 64) >> 3) + (fr >> 3);
;         const unsigned rowoff0 = (unsigned)(row0t + wr * 64 + fr) * (unsigned)(DFF * 2);
;         int cl = wc * 32 + 8 * fq; asm volatile("" : "+v"(cl));
;         const int ca = u.pn * 128 + cl;
;         if (t >= DECS - 2) {
.LBB0_1310:
	s_or_b64 exec, exec, s[0:1]
	v_fmamk_f32 v60, v144, 0x3a800000, v227
	v_mul_f32_e32 v61, 0x4b800000, v60
	v_cmp_gt_f32_e32 vcc, s76, v60
	v_fmamk_f32 v18, v18, 0x3a800000, v227
	s_lshl_b32 s0, s2, 5
	v_cndmask_b32_e32 v60, v60, v61, vcc
	v_rsq_f32_e32 v60, v60
	s_waitcnt lgkmcnt(0)
	s_barrier
	v_mul_f32_e32 v61, 0x45800000, v60
	v_cndmask_b32_e32 v60, v60, v61, vcc
	v_pk_mul_f32 v[170:171], v[134:135], v[60:61] op_sel_hi:[1,0]
	v_pk_mul_f32 v[168:169], v[132:133], v[60:61] op_sel_hi:[1,0]
	v_pk_mul_f32 v[126:127], v[126:127], v[60:61] op_sel_hi:[1,0]
	v_pk_mul_f32 v[124:125], v[124:125], v[60:61] op_sel_hi:[1,0]
	v_pk_mul_f32 v[94:95], v[94:95], v[60:61] op_sel_hi:[1,0]
	v_fmamk_f32 v61, v143, 0x3a800000, v227
	v_mul_f32_e32 v62, 0x4b800000, v61
	v_cmp_gt_f32_e32 vcc, s76, v61
	s_ashr_i32 s1, s4, 3
	s_mul_i32 s50, s53, 0x160000
	v_cndmask_b32_e32 v61, v61, v62, vcc
	v_rsq_f32_e32 v61, v61
	s_nop 0
	v_pk_mul_f32 v[92:93], v[92:93], v[60:61] op_sel_hi:[1,0]
	v_pk_mul_f32 v[66:67], v[122:123], v[60:61] op_sel_hi:[1,0]
	v_pk_mul_f32 v[64:65], v[120:121], v[60:61] op_sel_hi:[1,0]
	v_mul_f32_e32 v60, 0x45800000, v61
	v_cndmask_b32_e32 v60, v61, v60, vcc
	v_pk_mul_f32 v[166:167], v[118:119], v[60:61] op_sel_hi:[1,0]
	v_pk_mul_f32 v[164:165], v[116:117], v[60:61] op_sel_hi:[1,0]
	v_pk_mul_f32 v[122:123], v[114:115], v[60:61] op_sel_hi:[1,0]
	v_pk_mul_f32 v[120:121], v[112:113], v[60:61] op_sel_hi:[1,0]
	v_pk_mul_f32 v[90:91], v[90:91], v[60:61] op_sel_hi:[1,0]
	v_fmamk_f32 v61, v142, 0x3a800000, v227
	v_mul_f32_e32 v62, 0x4b800000, v61
	v_cmp_gt_f32_e32 vcc, s76, v61
	s_nop 1
	v_cndmask_b32_e32 v61, v61, v62, vcc
	v_rsq_f32_e32 v112, v61
	v_pk_mul_f32 v[88:89], v[88:89], v[60:61] op_sel_hi:[1,0]
	v_pk_mul_f32 v[62:63], v[110:111], v[60:61] op_sel_hi:[1,0]
	v_pk_mul_f32 v[60:61], v[108:109], v[60:61] op_sel_hi:[1,0]
	v_mul_f32_e32 v108, 0x45800000, v112
	v_cndmask_b32_e32 v108, v112, v108, vcc
	v_pk_mul_f32 v[116:117], v[100:101], v[108:109] op_sel_hi:[1,0]
	v_fmamk_f32 v100, v141, 0x3a800000, v227
	v_mul_f32_e32 v101, 0x4b800000, v100
	v_cmp_gt_f32_e32 vcc, s76, v100
	v_pk_mul_f32 v[106:107], v[106:107], v[108:109] op_sel_hi:[1,0]
	v_pk_mul_f32 v[104:105], v[104:105], v[108:109] op_sel_hi:[1,0]
	v_cndmask_b32_e32 v100, v100, v101, vcc
	v_rsq_f32_e32 v100, v100
	v_pk_mul_f32 v[118:119], v[102:103], v[108:109] op_sel_hi:[1,0]
	v_pk_mul_f32 v[86:87], v[86:87], v[108:109] op_sel_hi:[1,0]
	v_pk_mul_f32 v[84:85], v[84:85], v[108:109] op_sel_hi:[1,0]
	v_mul_f32_e32 v101, 0x45800000, v100
	v_cndmask_b32_e32 v100, v100, v101, vcc
	v_pk_mul_f32 v[132:133], v[76:77], v[100:101] op_sel_hi:[1,0]
	v_fmamk_f32 v76, v140, 0x3a800000, v227
	v_mul_f32_e32 v77, 0x4b800000, v76
	v_cmp_gt_f32_e32 vcc, s76, v76
	v_pk_mul_f32 v[148:149], v[80:81], v[100:101] op_sel_hi:[1,0]
	v_pk_mul_f32 v[58:59], v[58:59], v[108:109] op_sel_hi:[1,0]
	v_cndmask_b32_e32 v76, v76, v77, vcc
	v_rsq_f32_e32 v76, v76
	v_pk_mul_f32 v[56:57], v[56:57], v[108:109] op_sel_hi:[1,0]
	v_pk_mul_f32 v[150:151], v[82:83], v[100:101] op_sel_hi:[1,0]
	v_pk_mul_f32 v[134:135], v[78:79], v[100:101] op_sel_hi:[1,0]
	v_mul_f32_e32 v77, 0x45800000, v76
	v_cndmask_b32_e32 v80, v76, v77, vcc
	v_pk_mul_f32 v[76:77], v[44:45], v[80:81] op_sel_hi:[1,0]
	v_mul_f32_e32 v44, 0x4b800000, v18
	v_cmp_gt_f32_e32 vcc, s76, v18
	v_pk_mul_f32 v[144:145], v[48:49], v[80:81] op_sel_hi:[1,0]
	v_pk_mul_f32 v[48:49], v[40:41], v[80:81] op_sel_hi:[1,0]
	v_cndmask_b32_e32 v18, v18, v44, vcc
	v_rsq_f32_e32 v18, v18
	v_pk_mul_f32 v[146:147], v[50:51], v[80:81] op_sel_hi:[1,0]
	v_pk_mul_f32 v[78:79], v[46:47], v[80:81] op_sel_hi:[1,0]
	v_pk_mul_f32 v[12:13], v[12:13], v[80:81] op_sel_hi:[1,0]
	v_mul_f32_e32 v40, 0x45800000, v18
	v_cndmask_b32_e32 v18, v18, v40, vcc
	v_pk_mul_f32 v[10:11], v[10:11], v[80:81] op_sel_hi:[1,0]
	v_pk_mul_f32 v[50:51], v[42:43], v[80:81] op_sel_hi:[1,0]
	v_pk_mul_f32 v[142:143], v[38:39], v[18:19] op_sel_hi:[1,0]
	v_pk_mul_f32 v[140:141], v[36:37], v[18:19] op_sel_hi:[1,0]
	v_pk_mul_f32 v[82:83], v[30:31], v[18:19] op_sel_hi:[1,0]
	v_pk_mul_f32 v[80:81], v[28:29], v[18:19] op_sel_hi:[1,0]
	v_pk_mul_f32 v[8:9], v[8:9], v[18:19] op_sel_hi:[1,0]
	v_pk_mul_f32 v[6:7], v[6:7], v[18:19] op_sel_hi:[1,0]
	v_pk_mul_f32 v[46:47], v[26:27], v[18:19] op_sel_hi:[1,0]
	v_pk_mul_f32 v[44:45], v[24:25], v[18:19] op_sel_hi:[1,0]
	v_and_b32_e32 v108, 7, v222
	v_ashrrev_i32_e32 v18, 3, v222
	v_lshl_add_u32 v24, v223, 3, s0
	v_readlane_b32 s0, v244, 41
	v_pk_mul_f32 v[16:17], v[16:17], v[100:101] op_sel_hi:[1,0]
	v_pk_mul_f32 v[14:15], v[14:15], v[100:101] op_sel_hi:[1,0]
	v_pk_mul_f32 v[54:55], v[54:55], v[100:101] op_sel_hi:[1,0]
	v_pk_mul_f32 v[52:53], v[52:53], v[100:101] op_sel_hi:[1,0]
	v_cmp_lt_u32_e32 vcc, 5, v108
	v_add_u32_e32 v175, s0, v24
	v_add_lshl_u32 v28, v18, s1, 1
	v_add_u32_e32 v196, v108, v28
;     __device__ __forceinline__ void sample(f32x4 (&acc)[2][2][4][2], const Unit& u, int row0t, int wr, int wc, int fr, int fq) const {
;     ...
;         const unsigned stoff = (unsigned)((sql * 2 + (t & 1)) * DFF2 + ca) * 4u;
; #pragma unroll
;         for (int n = 0; n < 2; ++n) {
;             const unsigned cso = (unsigned)((ca + 4 * n) * 4);
;             const f32x4 w0 = *(const f32x4*)((const char*)cw + cso), w1 = *(const f32x4*)((const char*)(cw + DFF2) + cso), w2 = *(const f32x4*)((const char*)(cw + 2 * DFF2) + cso), bsv = *(const f32x4*)((const char*)cb + cso);
; #pragma unroll
;             for (int ai = 0; ai < 2; ++ai) {
; #pragma unroll
;                 for (int mp = 0; mp < 4; mp += 4) {
;                     f32x4 pv[4];
; #pragma unroll
;                     for (int k = 0; k < 4; ++k) { pv[k] = (f32x4){0.f, 0.f, 0.f, 0.f}; if (t < 2) pv[k] = *(const f32x4*)((const char*)st + stoff + (unsigned)(((16 * ai + 2 * (mp + k)) * 2 * DFF2 + 4 * n) * 4)); }
.LBB0_1312:
	v_readlane_b32 s4, v245, 3
	v_readlane_b32 s8, v245, 7
	v_readlane_b32 s9, v245, 8
	v_readlane_b32 s10, v245, 9
	v_readlane_b32 s11, v245, 10
	v_readlane_b32 s12, v245, 11
	v_readlane_b32 s13, v245, 12
	v_readlane_b32 s14, v245, 13
	v_readlane_b32 s15, v245, 14
	s_mov_b64 s[8:9], s[12:13]
	s_lshl_b64 s[0:1], s[50:51], 2
	s_mov_b64 s[10:11], s[14:15]
	s_add_u32 s2, s10, s0
	s_addc_u32 s3, s11, s1
	s_add_u32 s0, s96, 0x5800
	s_addc_u32 s1, s97, 0
	v_lshlrev_b32_e32 v176, 2, v175
	s_add_u32 s8, s96, 0xb000
	s_addc_u32 s9, s97, 0
	global_load_dwordx4 v[152:155], v176, s[0:1]
	global_load_dwordx4 v[156:159], v176, s[8:9]
	global_load_dwordx4 v[24:27], v176, s[96:97]
	global_load_dwordx4 v[160:163], v176, s[66:67]
	v_and_or_b32 v18, v222, 1, v28
	s_movk_i32 s4, 0x1600
	v_mul_lo_u32 v18, v18, s4
	v_readlane_b32 s5, v245, 4
	v_add_lshl_u32 v18, v175, v18, 2
	v_readlane_b32 s6, v245, 5
	v_readlane_b32 s7, v245, 6
	v_cmp_gt_u32_e64 s[4:5], 2, v108
	v_lshl_add_u64 v[172:173], s[2:3], 0, v[18:19]
	v_mov_b32_e32 v36, 0
	v_mov_b32_e32 v100, 0
	v_mov_b32_e32 v101, 0
	v_mov_b32_e32 v102, 0
	v_mov_b32_e32 v103, 0
	v_readlane_b32 s16, v245, 15
	v_readlane_b32 s17, v245, 16
	v_readlane_b32 s18, v245, 17
	v_readlane_b32 s19, v245, 18
	v_mov_b32_e32 v178, 0
	v_mov_b32_e32 v179, 0
	v_mov_b32_e32 v180, 0
	v_mov_b32_e32 v181, 0
	v_mov_b32_e32 v182, 0
	v_mov_b32_e32 v183, 0
	v_mov_b32_e32 v184, 0
	v_mov_b32_e32 v185, 0
	v_mov_b32_e32 v186, 0
	v_mov_b32_e32 v187, 0
	v_mov_b32_e32 v188, 0
	v_mov_b32_e32 v189, 0
	v_mov_b32_e32 v190, 0
	v_mov_b32_e32 v191, 0
	v_mov_b32_e32 v192, 0
	v_mov_b32_e32 v193, 0
	s_and_saveexec_b64 s[100:101], s[4:5]
	s_cbranch_execz .Lspp_0
	global_load_dwordx4 v[178:181], v[172:173], off
	s_mov_b64 s[98:99], 0x16000
	v_lshl_add_u64 v[194:195], v[172:173], 0, s[98:99]
	global_load_dwordx4 v[182:185], v[194:195], off
	s_mov_b64 s[98:99], 0x2c000
	v_lshl_add_u64 v[194:195], v[172:173], 0, s[98:99]
	global_load_dwordx4 v[186:189], v[194:195], off
	s_mov_b64 s[98:99], 0x42000
	v_lshl_add_u64 v[194:195], v[172:173], 0, s[98:99]
	global_load_dwordx4 v[190:193], v[194:195], off
;     __device__ __forceinline__ void sample(f32x4 (&acc)[2][2][4][2], const Unit& u, int row0t, int wr, int wc, int fr, int fq) const {
;     ...
;         if (t >= DECS - 2) {
; #pragma unroll
;             for (int ai = 0; ai < 2; ++ai)
; #pragma unroll
;                 for (int m = 0; m < 4; ++m) { const unsigned oo = (unsigned)(((sql + 16 * ai + 2 * m) * 2 + (t - (DECS - 2))) * DFF2 + ca) * 4u;
; #pragma unroll
;                     for (int bj = 0; bj < 2; ++bj)
; #pragma unroll
;                         for (int n = 0; n < 2; ++n) *(f32x4*)((char*)outs + oo + (unsigned)((bj * DFF + 4 * n) * 4)) = acc[ai][bj][m][n]; }
;             asm volatile("" ::: "memory");
;         }
;     ...
;                     f32x4 pv[4];
; #pragma unroll
;                     for (int k = 0; k < 4; ++k) { pv[k] = (f32x4){0.f, 0.f, 0.f, 0.f}; if (t < 2) pv[k] = *(const f32x4*)((const char*)st + stoff + (unsigned)(((16 * ai + 2 * (mp + k)) * 2 * DFF2 + 4 * n) * 4)); }
; #pragma unroll
;                     for (int k = 0; k < 4; ++k) acc[ai][0][mp + k][n] = conv4s(acc[ai][0][mp + k][n], pv[k], t, w0, w1, w2, bsv);
.Lspp_0:
	s_or_b64 exec, exec, s[100:101]
	s_nop 4
	v_mov_b32_e32 v37, 0
	v_mov_b32_e32 v38, 0
	v_mov_b32_e32 v39, 0
	v_mov_b32_e32 v28, 0
	v_mov_b32_e32 v40, 0
	v_mov_b32_e32 v41, 0
	v_mov_b32_e32 v42, 0
	v_mov_b32_e32 v43, 0
	v_mov_b32_e32 v29, 0
	v_mov_b32_e32 v30, 0
	v_mov_b32_e32 v31, 0
	s_nop 0
	s_nop 0
	v_mov_b32_e32 v110, v19
	v_mov_b32_dpp v18, v168 row_shr:1 row_mask:0xf bank_mask:0xf bound_ctrl:1
	v_mov_b32_dpp v109, v168 row_shr:2 row_mask:0xf bank_mask:0xf bound_ctrl:1
	s_waitcnt vmcnt(0)
	v_cmp_lt_u32_e32 vcc, 5, v108
	v_mov_b32_e32 v203, 0
	s_nop 1
	s_and_saveexec_b64 s[26:27], vcc
	s_cbranch_execz .Lss_skip
	s_lshl_b64 s[22:23], s[50:51], 2
	v_readlane_b32 s20, v245, 58
	s_add_u32 s20, s20, s22
	v_readlane_b32 s22, v245, 59
	s_addc_u32 s21, s22, s23
	v_mov_b32_e32 v202, v196
	s_movk_i32 s22, 0x1600
	v_mul_lo_u32 v202, v202, s22
	v_add_lshl_u32 v197, v202, v175, 2
	v_add_u32_e32 v202, 0xfffdf000, v197
	v_lshl_add_u64 v[224:225], s[20:21], 0, v[202:203]
	s_movk_i32 s22, 0x2000
	v_add_co_u32_e32 v224, vcc, s22, v224
	global_store_dwordx4 v202, v[168:171], s[20:21]
	global_store_dwordx4 v202, v[124:127], s[20:21] offset:16
	v_addc_co_u32_e32 v225, vcc, 0, v225, vcc
	v_add_u32_e32 v202, 0xffff5000, v197
	global_store_dwordx4 v[224:225], v[92:95], off offset:3072
	global_store_dwordx4 v[224:225], v[64:67], off offset:3088
	v_lshl_add_u64 v[224:225], s[20:21], 0, v[202:203]
	v_add_co_u32_e32 v224, vcc, s22, v224
	global_store_dwordx4 v202, v[164:167], s[20:21]
	global_store_dwordx4 v202, v[120:123], s[20:21] offset:16
	v_addc_co_u32_e32 v225, vcc, 0, v225, vcc
	v_add_u32_e32 v202, 0xb000, v197
	global_store_dwordx4 v[224:225], v[88:91], off offset:3072
	global_store_dwordx4 v[224:225], v[60:63], off offset:3088
	v_lshl_add_u64 v[224:225], s[20:21], 0, v[202:203]
	v_add_co_u32_e32 v224, vcc, s22, v224
	global_store_dwordx4 v202, v[104:107], s[20:21]
	global_store_dwordx4 v202, v[116:119], s[20:21] offset:16
	v_addc_co_u32_e32 v225, vcc, 0, v225, vcc
	v_add_u32_e32 v202, 0x21000, v197
	global_store_dwordx4 v[224:225], v[84:87], off offset:3072
	global_store_dwordx4 v[224:225], v[56:59], off offset:3088
	v_lshl_add_u64 v[224:225], s[20:21], 0, v[202:203]
	v_add_co_u32_e32 v224, vcc, s22, v224
	global_store_dwordx4 v202, v[136:139], s[20:21]
	global_store_dwordx4 v202, v[72:75], s[20:21] offset:16
	v_addc_co_u32_e32 v225, vcc, 0, v225, vcc
	v_add_u32_e32 v202, 0x8f000, v197
	global_store_dwordx4 v[224:225], v[68:71], off offset:3072
	global_store_dwordx4 v[224:225], v[32:35], off offset:3088
	v_lshl_add_u64 v[224:225], s[20:21], 0, v[202:203]
	v_add_co_u32_e32 v224, vcc, s22, v224
	global_store_dwordx4 v202, v[148:151], s[20:21]
	global_store_dwordx4 v202, v[132:135], s[20:21] offset:16
	v_addc_co_u32_e32 v225, vcc, 0, v225, vcc
	v_add_u32_e32 v202, 0xa5000, v197
	global_store_dwordx4 v[224:225], v[14:17], off offset:3072
	global_store_dwordx4 v[224:225], v[52:55], off offset:3088
	v_lshl_add_u64 v[224:225], s[20:21], 0, v[202:203]
	v_add_co_u32_e32 v224, vcc, s22, v224
	global_store_dwordx4 v202, v[144:147], s[20:21]
	global_store_dwordx4 v202, v[76:79], s[20:21] offset:16
	v_addc_co_u32_e32 v225, vcc, 0, v225, vcc
	v_add_u32_e32 v202, 0xbb000, v197
	global_store_dwordx4 v[224:225], v[10:13], off offset:3072
	global_store_dwordx4 v[224:225], v[48:51], off offset:3088
	v_lshl_add_u64 v[224:225], s[20:21], 0, v[202:203]
	v_add_co_u32_e32 v224, vcc, s22, v224
	global_store_dwordx4 v202, v[140:143], s[20:21]
	global_store_dwordx4 v202, v[80:83], s[20:21] offset:16
	v_addc_co_u32_e32 v225, vcc, 0, v225, vcc
	v_add_u32_e32 v202, 0xd1000, v197
	global_store_dwordx4 v[224:225], v[6:9], off offset:3072
	global_store_dwordx4 v[224:225], v[44:47], off offset:3088
	v_lshl_add_u64 v[224:225], s[20:21], 0, v[202:203]
	v_add_co_u32_e32 v224, vcc, 0x2000, v224
	global_store_dwordx4 v202, v[128:131], s[20:21]
	global_store_dwordx4 v202, v[96:99], s[20:21] offset:16
	v_addc_co_u32_e32 v225, vcc, 0, v225, vcc
	global_store_dwordx4 v[224:225], v[2:5], off offset:3072
	global_store_dwordx4 v[224:225], v[20:23], off offset:3088
.Lss_skip:
	s_or_b64 exec, exec, s[26:27]
	s_nop 4
	v_mov_b32_e32 v204, 0
	v_mov_b32_e32 v205, 0
	v_mov_b32_e32 v206, 0
	v_mov_b32_e32 v207, 0
	v_mov_b32_e32 v208, 0
	v_mov_b32_e32 v209, 0
	v_mov_b32_e32 v210, 0
	v_mov_b32_e32 v211, 0
	v_mov_b32_e32 v212, 0
	v_mov_b32_e32 v213, 0
	v_mov_b32_e32 v214, 0
	v_mov_b32_e32 v215, 0
	v_mov_b32_e32 v216, 0
	v_mov_b32_e32 v217, 0
	v_mov_b32_e32 v218, 0
	v_mov_b32_e32 v219, 0
	s_and_saveexec_b64 s[100:101], s[4:5]
	s_cbranch_execz .Lspp_1
	s_mov_b64 s[98:99], 0xb0000
	v_lshl_add_u64 v[194:195], v[172:173], 0, s[98:99]
	global_load_dwordx4 v[204:207], v[194:195], off
	s_mov_b64 s[98:99], 0xc6000
	v_lshl_add_u64 v[194:195], v[172:173], 0, s[98:99]
	global_load_dwordx4 v[208:211], v[194:195], off
	s_mov_b64 s[98:99], 0xdc000
	v_lshl_add_u64 v[194:195], v[172:173], 0, s[98:99]
	global_load_dwordx4 v[212:215], v[194:195], off
	s_mov_b64 s[98:99], 0xf2000
	v_lshl_add_u64 v[194:195], v[172:173], 0, s[98:99]
	global_load_dwordx4 v[216:219], v[194:195], off
